# GEMM: no per-phase flips; one static s_setprio 1 for the wr==1 wave group (waves 4-7) for the whole GEMM, reset to 0 after the final barriers
# baseline (speedup 1.0000x reference)
; #define PG8_STAGE(bufoff, gbase, voff) do { _Pragma("unroll") for (int _i = 0; _i < 2; ++_i) \
;     __builtin_amdgcn_global_load_lds((const unsigned*)((const char*)(gbase) + (voff)[_i]), (LAS unsigned*)(lds + (bufoff) + ldsw + _i * 8192), 16, 0, 0); } while (0)
; #define PG8_BAR __builtin_amdgcn_s_barrier()
; template <class Epi>
; DI void gemm_phase(LAS unsigned char* lds, const Gemm g, const StaticOrder& S, const Epi& E) {
;     ...
;   for (int i = 0; i < 2; ++i) { int R, C; stage_rc(tid * 16 + i * 8192, R, C); const int Rb = (R & ~31) + perm32(R & 31);
;     voffA[i] = (unsigned)(R * lda + C) * 2u; voffB[i] = (unsigned)(Rb * K + C) * 2u; }
;   const size_t kstep = (size_t)(BK * 2);
;   const size_t hstepA = (size_t)HALF * lda * 2, hstepB = (size_t)HALF * K * 2;
;   const size_t tstepA = 2 * hstepA, tstepB = 2 * hstepB;
;   const unsigned ldsw = (unsigned)wid * 1024u;
;   const int aoff = lds_byte(wr * 64 + fr, fq * 8), boff = lds_byte(wc * 32 + fr, fq * 8);
;     ...
;   bf16x8 At[4][2], B0[2][2], B1[2][2];
;   const char* cA = (const char*)g.A + (size_t)cur.pm * tstepA; const char* cB = (const char*)g.Bt + (size_t)cur.pn * tstepB;
;   PG8_STAGE(PG8_SB(0, 0), cB, voffB); PG8_STAGE(PG8_SA(0, 0), cA, voffA); PG8_STAGE(PG8_SB(0, 1), cB + hstepB, voffB); PG8_STAGE(PG8_SA(0, 1), cA + hstepA, voffA);
;   if (wr == 1) PG8_BAR;
.LBB0_177:
	v_lshrrev_b32_e32 v4, 1, v141
	v_lshrrev_b32_e32 v5, 5, v141
	v_lshlrev_b32_e32 v2, 4, v141
	v_and_b32_e32 v3, 32, v141
	v_bfe_u32 v12, v141, 2, 4
	v_and_b32_e32 v4, 24, v4
	v_and_b32_e32 v5, 4, v5
	v_bfe_u32 v6, v141, 2, 2
	s_movk_i32 s0, 0x70
	v_bitop3_b32 v10, v2, v3, 48 bitop3:0x6c
	v_and_b32_e32 v11, 64, v141
	v_or3_b32 v4, v5, v6, v4
	v_and_or_b32 v5, v1, s0, v12
	s_movk_i32 s0, 0x60
	v_add_u32_e32 v13, 0x2000, v2
	s_add_u32 s42, s84, 0x17800000
	v_or_b32_e32 v3, v10, v11
	v_and_or_b32 v6, v1, s0, v4
	v_lshrrev_b32_e32 v2, 7, v13
	s_movk_i32 s0, 0xf0
	s_addc_u32 s43, s85, 0
	s_lshr_b32 s1, s33, 6
	v_lshl_or_b32 v130, v5, 12, v3
	v_and_or_b32 v5, v2, s0, v12
	s_movk_i32 s0, 0xe0
	s_ashr_i32 s5, s4, 31
	s_ashr_i32 s37, s36, 31
	v_and_or_b32 v2, v2, s0, v4
	s_lshr_b32 s0, s33, 8
	s_lshl_b32 s44, s1, 10
	s_lshl_b64 s[2:3], s[4:5], 20
	s_lshl_b64 s[6:7], s[36:37], 20
	s_add_u32 s30, s84, s6
	s_addc_u32 s31, s85, s7
	s_add_i32 s45, s44, 0
	v_lshl_or_b32 v132, v6, 12, v3
	s_add_i32 m0, s45, 0x10000
	v_lshl_or_b32 v136, v2, 12, v3
	global_load_lds_dwordx4 v132, s[30:31]
	s_add_i32 m0, s45, 0x12000
	s_add_u32 s6, s42, s2
	global_load_lds_dwordx4 v136, s[30:31]
	s_addc_u32 s7, s43, s3
	s_mov_b32 m0, s45
	s_add_i32 s46, s45, 0x2000
	v_lshl_or_b32 v134, v5, 12, v3
	global_load_lds_dwordx4 v130, s[6:7]
	s_mov_b32 m0, s46
	s_add_u32 s2, s30, 0x80000
	global_load_lds_dwordx4 v134, s[6:7]
	s_addc_u32 s3, s31, 0
	s_add_i32 m0, s45, 0x14000
	v_mov_b32_e32 v139, 0
	global_load_lds_dwordx4 v132, s[2:3]
	s_add_i32 m0, s45, 0x16000
	v_mov_b32_e32 v133, v139
	global_load_lds_dwordx4 v136, s[2:3]
	s_add_u32 s2, s6, 0x80000
	s_addc_u32 s3, s7, 0
	s_add_i32 s47, s45, 0x4000
	s_mov_b32 m0, s47
	s_add_i32 s48, s45, 0x6000
	global_load_lds_dwordx4 v130, s[2:3]
	s_mov_b32 m0, s48
	v_mov_b32_e32 v137, v139
	global_load_lds_dwordx4 v134, s[2:3]
	v_mov_b32_e32 v131, v139
	v_mov_b32_e32 v135, v139
	s_mov_b32 s9, 0
	v_lshl_add_u64 v[8:9], s[30:31], 0, v[132:133]
	v_lshl_add_u64 v[6:7], s[30:31], 0, v[136:137]
	v_lshl_add_u64 v[4:5], s[6:7], 0, v[130:131]
	s_cmp_lg_u32 s0, 1
	v_lshl_add_u64 v[2:3], s[6:7], 0, v[134:135]
	s_cbranch_scc1 .LBB0_179
	s_setprio 1
	s_barrier

; #define PG8_WAIT_V(n) asm volatile("s_waitcnt vmcnt(" #n ")" ::: "memory")
; #define PG8_BAR __builtin_amdgcn_s_barrier()
; DI void conv_idle_round(const Params& p, char* lds) {
;   if (blockIdx.x < 128) return;
; template <class Epi>
; DI void gemm_phase(LAS unsigned char* lds, const Gemm g, const StaticOrder& S, const Epi& E) {
;     ...
;   PG8_WAIT_V(0);
;   if (wr == 0) PG8_BAR;
;   PG8_BAR;
.LBB0_331:
	s_barrier
	s_setprio 0
	s_cmpk_lt_u32 s60, 0x80
	s_cbranch_scc1 .LBB0_421

; #define PG8_STAGE(bufoff, gbase, voff) do { _Pragma("unroll") for (int _i = 0; _i < 2; ++_i) \
;     __builtin_amdgcn_global_load_lds((const unsigned*)((const char*)(gbase) + (voff)[_i]), (LAS unsigned*)(lds + (bufoff) + ldsw + _i * 8192), 16, 0, 0); } while (0)
; template <class Epi>
; DI void gemm_phase(LAS unsigned char* lds, const Gemm g, const StaticOrder& S, const Epi& E) {
;     ...
;   for (int i = 0; i < 2; ++i) { int R, C; stage_rc(tid * 16 + i * 8192, R, C); const int Rb = (R & ~31) + perm32(R & 31);
;     voffA[i] = (unsigned)(R * lda + C) * 2u; voffB[i] = (unsigned)(Rb * K + C) * 2u; }
;   const size_t kstep = (size_t)(BK * 2);
;   const size_t hstepA = (size_t)HALF * lda * 2, hstepB = (size_t)HALF * K * 2;
;   const size_t tstepA = 2 * hstepA, tstepB = 2 * hstepB;
;   const unsigned ldsw = (unsigned)wid * 1024u;
;   const int aoff = lds_byte(wr * 64 + fr, fq * 8), boff = lds_byte(wc * 32 + fr, fq * 8);
;     ...
;   if (!S.next(0, cur)) return;
;   f32x4 acc[2][2][4][2];
; #pragma unroll
;   for (int a = 0; a < 2; ++a)
; #pragma unroll
;     for (int b = 0; b < 2; ++b)
; #pragma unroll
;       for (int m = 0; m < 4; ++m)
; #pragma unroll
;         for (int n = 0; n < 2; ++n) acc[a][b][m][n] = (f32x4){0.f, 0.f, 0.f, 0.f};
;   bf16x8 At[4][2], B0[2][2], B1[2][2];
;   const char* cA = (const char*)g.A + (size_t)cur.pm * tstepA; const char* cB = (const char*)g.Bt + (size_t)cur.pn * tstepB;
;   PG8_STAGE(PG8_SB(0, 0), cB, voffB); PG8_STAGE(PG8_SA(0, 0), cA, voffA); PG8_STAGE(PG8_SB(0, 1), cB + hstepB, voffB); PG8_STAGE(PG8_SA(0, 1), cA + hstepA, voffA);
.LBB0_476:
	v_lshrrev_b32_e32 v4, 5, v1
	v_lshrrev_b32_e32 v6, 1, v1
	v_and_b32_e32 v4, 4, v4
	v_bfe_u32 v5, v1, 2, 2
	v_and_b32_e32 v168, 24, v6
	v_lshlrev_b32_e32 v2, 4, v1
	v_and_b32_e32 v3, 32, v1
	v_bfe_u32 v141, v1, 2, 4
	v_or3_b32 v4, v4, v5, v168
	v_lshrrev_b32_e32 v5, 3, v1
	s_movk_i32 s3, 0x70
	v_bitop3_b32 v143, v2, v3, 48 bitop3:0x6c
	v_and_b32_e32 v166, 64, v1
	v_and_or_b32 v6, v5, s3, v141
	s_movk_i32 s3, 0x60
	v_add_u32_e32 v167, 0x2000, v2
	v_or_b32_e32 v3, v143, v166
	v_and_or_b32 v5, v5, s3, v4
	v_lshrrev_b32_e32 v2, 7, v167
	s_movk_i32 s3, 0xf0
	v_lshl_or_b32 v132, v5, 10, v3
	v_and_or_b32 v5, v2, s3, v141
	s_movk_i32 s3, 0xe0
	v_and_or_b32 v2, v2, s3, v4
	v_lshl_or_b32 v130, v6, 11, v3
	v_lshl_or_b32 v134, v5, 11, v3
	v_lshl_or_b32 v136, v2, 10, v3
	v_lshlrev_b32_e32 v2, 6, v1
	v_lshlrev_b32_e32 v3, 2, v1
	v_lshlrev_b32_e32 v170, 1, v168
	v_and_b32_e32 v2, 0x3c0, v2
	v_and_b32_e32 v3, 32, v3
	v_and_b32_e32 v169, 15, v1
	s_andn2_b64 vcc, exec, s[0:1]
	v_bitop3_b32 v171, v170, v3, v2 bitop3:0x36
	s_cbranch_vccnz .LBB0_552
	s_add_u32 s35, s84, 0x13800000
	s_addc_u32 s36, s85, 0
	s_add_u32 s37, s84, 0x1100000
	s_addc_u32 s38, s85, 0
	s_lshr_b32 s1, s34, 6
	s_ashr_i32 s5, s4, 31
	s_ashr_i32 s3, s2, 31
	s_lshr_b32 s0, s34, 8
	s_lshl_b32 s39, s1, 10
	s_lshl_b64 s[6:7], s[4:5], 19
	s_lshl_b64 s[8:9], s[2:3], 18
	s_add_u32 s28, s37, s8
	s_addc_u32 s29, s38, s9
	s_add_i32 s40, s39, 0
	s_add_i32 m0, s40, 0x10000
	v_mov_b32_e32 v139, 0
	global_load_lds_dwordx4 v132, s[28:29]
	s_add_i32 m0, s40, 0x12000
	s_add_u32 s26, s35, s6
	global_load_lds_dwordx4 v136, s[28:29]
	s_addc_u32 s27, s36, s7
	s_mov_b32 m0, s40
	s_add_i32 s41, s40, 0x2000
	global_load_lds_dwordx4 v130, s[26:27]
	s_mov_b32 m0, s41
	s_add_u32 s6, s28, 0x20000
	global_load_lds_dwordx4 v134, s[26:27]
	s_addc_u32 s7, s29, 0
	s_add_i32 m0, s40, 0x14000
	v_mov_b32_e32 v133, v139
	global_load_lds_dwordx4 v132, s[6:7]
	s_add_i32 m0, s40, 0x16000
	v_mov_b32_e32 v137, v139
	global_load_lds_dwordx4 v136, s[6:7]
	s_add_u32 s6, s26, 0x40000
	s_addc_u32 s7, s27, 0
	s_add_i32 s42, s40, 0x4000
	s_mov_b32 m0, s42
	s_add_i32 s43, s40, 0x6000
	global_load_lds_dwordx4 v130, s[6:7]
	s_mov_b32 m0, s43
	v_mov_b32_e32 v131, v139
	global_load_lds_dwordx4 v134, s[6:7]
	v_mov_b32_e32 v135, v139
	s_mov_b32 s7, 0
	v_lshl_add_u64 v[8:9], s[28:29], 0, v[132:133]
	v_lshl_add_u64 v[6:7], s[28:29], 0, v[136:137]
	v_lshl_add_u64 v[4:5], s[26:27], 0, v[130:131]
	v_lshl_add_u64 v[2:3], s[26:27], 0, v[134:135]
	s_cmp_lg_u32 s0, 1
	s_movk_i32 s44, 0x4000
	s_cbranch_scc1 .LBB0_479
	s_setprio 1
	s_barrier

; #define PG8_WAIT_V(n) asm volatile("s_waitcnt vmcnt(" #n ")" ::: "memory")
; #define PG8_BAR __builtin_amdgcn_s_barrier()
; template <class Epi>
; DI void gemm_phase(LAS unsigned char* lds, const Gemm g, const StaticOrder& S, const Epi& E) {
;     ...
;   PG8_WAIT_V(0);
;   if (wr == 0) PG8_BAR;
;   PG8_BAR;
.LBB0_551:
	s_barrier
	s_setprio 0

; #define PG8_STAGE(bufoff, gbase, voff) do { _Pragma("unroll") for (int _i = 0; _i < 2; ++_i) \
;     __builtin_amdgcn_global_load_lds((const unsigned*)((const char*)(gbase) + (voff)[_i]), (LAS unsigned*)(lds + (bufoff) + ldsw + _i * 8192), 16, 0, 0); } while (0)
; #define PG8_BAR __builtin_amdgcn_s_barrier()
;   DI bool next(int i, Unit& u) const {
;     const long L = (long)i * G + c; if (L >= nwg) return false;
;     int wgid = (int)L; { const int q = nwg / NXCD, r = nwg % NXCD, xcd = wgid % NXCD, off = wgid / NXCD; wgid = (xcd < r ? xcd * (q + 1) : r * (q + 1) + (xcd - r) * q) + off; }
;     const int nig = wgm * nN, gid = wgid / nig, fm = gid * wgm, gsz = (nM - fm) < wgm ? (nM - fm) : wgm;
;     u.pm = fm + ((wgid % nig) % gsz); u.pn = (wgid % nig) / gsz; return true;
; template <class Epi>
; DI void gemm_phase(LAS unsigned char* lds, const Gemm g, const StaticOrder& S, const Epi& E) {
;     ...
;   bf16x8 At[4][2], B0[2][2], B1[2][2];
;   const char* cA = (const char*)g.A + (size_t)cur.pm * tstepA; const char* cB = (const char*)g.Bt + (size_t)cur.pn * tstepB;
;   PG8_STAGE(PG8_SB(0, 0), cB, voffB); PG8_STAGE(PG8_SA(0, 0), cA, voffA); PG8_STAGE(PG8_SB(0, 1), cB + hstepB, voffB); PG8_STAGE(PG8_SA(0, 1), cA + hstepA, voffA);
;   if (wr == 1) PG8_BAR;
.LBB0_557:
	s_ashr_i32 s0, s2, 3
	s_add_u32 s26, s84, 0x13800400
	s_addc_u32 s27, s85, 0
	s_add_u32 s28, s84, 0x1280000
	s_addc_u32 s29, s85, 0
	s_add_i32 s0, s3, s0
	s_ashr_i32 s3, s0, 31
	s_lshr_b32 s3, s3, 26
	s_add_i32 s3, s0, s3
	s_ashr_i32 s4, s3, 6
	s_andn2_b32 s3, s3, 63
	s_sub_i32 s3, s0, s3
	s_bfe_i32 s0, s3, 0x80000
	s_bfe_u32 s0, s0, 0x3000c
	s_add_i32 s5, s3, s0
	s_bfe_i32 s0, s5, 0x80000
	s_and_b32 s5, s5, 0xf8
	s_sub_i32 s3, s3, s5
	s_lshl_b32 s4, s4, 3
	s_sext_i32_i16 s0, s0
	s_sext_i32_i8 s3, s3
	s_lshr_b32 s1, s24, 8
	s_lshr_b32 s0, s0, 3
	s_add_i32 s16, s4, s3
	s_lshr_b32 s2, s24, 6
	s_ashr_i32 s17, s16, 31
	s_bfe_i64 s[6:7], s[0:1], 0x100000
	s_lshl_b32 s30, s2, 10
	s_lshl_b64 s[4:5], s[16:17], 19
	s_lshl_b64 s[6:7], s[6:7], 18
	s_add_u32 s20, s28, s6
	s_addc_u32 s21, s29, s7
	s_add_i32 s17, s30, 0
	s_add_i32 m0, s17, 0x10000
	v_mov_b32_e32 v139, 0
	global_load_lds_dwordx4 v132, s[20:21]
	s_add_i32 m0, s17, 0x12000
	s_add_u32 s22, s26, s4
	global_load_lds_dwordx4 v136, s[20:21]
	s_addc_u32 s23, s27, s5
	s_mov_b32 m0, s17
	s_add_i32 s31, s17, 0x2000
	global_load_lds_dwordx4 v130, s[22:23]
	s_mov_b32 m0, s31
	s_add_u32 s4, s20, 0x20000
	global_load_lds_dwordx4 v134, s[22:23]
	s_addc_u32 s5, s21, 0
	s_add_i32 m0, s17, 0x14000
	v_mov_b32_e32 v133, v139
	global_load_lds_dwordx4 v132, s[4:5]
	s_add_i32 m0, s17, 0x16000
	v_mov_b32_e32 v137, v139
	global_load_lds_dwordx4 v136, s[4:5]
	s_add_u32 s4, s22, 0x40000
	s_addc_u32 s5, s23, 0
	s_add_i32 s33, s17, 0x4000
	s_mov_b32 m0, s33
	s_add_i32 s34, s17, 0x6000
	global_load_lds_dwordx4 v130, s[4:5]
	s_mov_b32 m0, s34
	v_mov_b32_e32 v131, v139
	global_load_lds_dwordx4 v134, s[4:5]
	v_mov_b32_e32 v135, v139
	s_mov_b32 s35, 0
	v_lshl_add_u64 v[8:9], s[20:21], 0, v[132:133]
	v_lshl_add_u64 v[6:7], s[20:21], 0, v[136:137]
	v_lshl_add_u64 v[4:5], s[22:23], 0, v[130:131]
	s_cmp_lg_u32 s1, 1
	v_lshl_add_u64 v[2:3], s[22:23], 0, v[134:135]
	s_cbranch_scc1 .LBB0_559
	s_setprio 1
	s_barrier

; #define PG8_STAGE(bufoff, gbase, voff) do { _Pragma("unroll") for (int _i = 0; _i < 2; ++_i) \
;     __builtin_amdgcn_global_load_lds((const unsigned*)((const char*)(gbase) + (voff)[_i]), (LAS unsigned*)(lds + (bufoff) + ldsw + _i * 8192), 16, 0, 0); } while (0)
; #define PG8_BAR __builtin_amdgcn_s_barrier()
; template <class Epi>
; DI void gemm_phase(LAS unsigned char* lds, const Gemm g, const StaticOrder& S, const Epi& E) {
;     ...
;   for (int i = 0; i < 2; ++i) { int R, C; stage_rc(tid * 16 + i * 8192, R, C); const int Rb = (R & ~31) + perm32(R & 31);
;     voffA[i] = (unsigned)(R * lda + C) * 2u; voffB[i] = (unsigned)(Rb * K + C) * 2u; }
;   const size_t kstep = (size_t)(BK * 2);
;   const size_t hstepA = (size_t)HALF * lda * 2, hstepB = (size_t)HALF * K * 2;
;   const size_t tstepA = 2 * hstepA, tstepB = 2 * hstepB;
;   const unsigned ldsw = (unsigned)wid * 1024u;
;   const int aoff = lds_byte(wr * 64 + fr, fq * 8), boff = lds_byte(wc * 32 + fr, fq * 8);
;     ...
;   bf16x8 At[4][2], B0[2][2], B1[2][2];
;   const char* cA = (const char*)g.A + (size_t)cur.pm * tstepA; const char* cB = (const char*)g.Bt + (size_t)cur.pn * tstepB;
;   PG8_STAGE(PG8_SB(0, 0), cB, voffB); PG8_STAGE(PG8_SA(0, 0), cA, voffA); PG8_STAGE(PG8_SB(0, 1), cB + hstepB, voffB); PG8_STAGE(PG8_SA(0, 1), cA + hstepA, voffA);
;   if (wr == 1) PG8_BAR;
.LBB0_828:
	s_andn2_b64 vcc, exec, s[0:1]
	s_cbranch_vccnz .LBB0_860
	v_lshrrev_b32_e32 v3, 1, v10
	v_lshrrev_b32_e32 v4, 5, v10
	v_and_b32_e32 v3, 24, v3
	v_and_b32_e32 v4, 4, v4
	v_bfe_u32 v5, v10, 2, 2
	s_add_u32 s29, s84, 0x13800000
	v_lshlrev_b32_e32 v1, 4, v10
	v_and_b32_e32 v2, 32, v10
	v_bfe_u32 v13, v10, 2, 4
	v_or3_b32 v3, v4, v5, v3
	v_lshrrev_b32_e32 v4, 3, v10
	s_movk_i32 s0, 0x70
	s_addc_u32 s30, s85, 0
	v_bitop3_b32 v11, v1, v2, 48 bitop3:0x6c
	v_and_b32_e32 v12, 64, v10
	v_and_or_b32 v5, v4, s0, v13
	s_movk_i32 s0, 0x60
	v_add_u32_e32 v14, 0x2000, v1
	s_add_u32 s31, s84, 0x1480000
	v_or_b32_e32 v2, v11, v12
	v_and_or_b32 v4, v4, s0, v3
	v_lshrrev_b32_e32 v1, 7, v14
	s_movk_i32 s0, 0xf0
	s_addc_u32 s33, s85, 0
	s_lshr_b32 s1, s28, 6
	v_lshl_or_b32 v132, v4, 12, v2
	v_and_or_b32 v4, v1, s0, v13
	s_movk_i32 s0, 0xe0
	s_ashr_i32 s21, s20, 31
	s_ashr_i32 s5, s4, 31
	v_and_or_b32 v1, v1, s0, v3
	s_lshr_b32 s0, s28, 8
	s_lshl_b32 s34, s1, 10
	s_lshl_b64 s[2:3], s[20:21], 19
	s_lshl_b64 s[6:7], s[4:5], 20
	s_add_u32 s24, s31, s6
	s_addc_u32 s25, s33, s7
	s_add_i32 s35, s34, 0
	s_add_i32 m0, s35, 0x10000
	v_lshl_or_b32 v136, v1, 12, v2
	global_load_lds_dwordx4 v132, s[24:25]
	s_add_i32 m0, s35, 0x12000
	s_add_u32 s22, s29, s2
	v_lshl_or_b32 v130, v5, 11, v2
	global_load_lds_dwordx4 v136, s[24:25]
	s_addc_u32 s23, s30, s3
	s_mov_b32 m0, s35
	s_add_i32 s36, s35, 0x2000
	v_lshl_or_b32 v134, v4, 11, v2
	global_load_lds_dwordx4 v130, s[22:23]
	s_mov_b32 m0, s36
	s_add_u32 s2, s24, 0x80000
	global_load_lds_dwordx4 v134, s[22:23]
	s_addc_u32 s3, s25, 0
	s_add_i32 m0, s35, 0x14000
	v_mov_b32_e32 v139, 0
	global_load_lds_dwordx4 v132, s[2:3]
	s_add_i32 m0, s35, 0x16000
	v_mov_b32_e32 v133, v139
	global_load_lds_dwordx4 v136, s[2:3]
	s_add_u32 s2, s22, 0x40000
	s_addc_u32 s3, s23, 0
	s_add_i32 s37, s35, 0x4000
	s_mov_b32 m0, s37
	s_add_i32 s38, s35, 0x6000
	global_load_lds_dwordx4 v130, s[2:3]
	s_mov_b32 m0, s38
	v_mov_b32_e32 v137, v139
	global_load_lds_dwordx4 v134, s[2:3]
	v_mov_b32_e32 v131, v139
	v_mov_b32_e32 v135, v139
	s_mov_b32 s5, 0
	v_lshl_add_u64 v[8:9], s[24:25], 0, v[132:133]
	v_lshl_add_u64 v[6:7], s[24:25], 0, v[136:137]
	v_lshl_add_u64 v[4:5], s[22:23], 0, v[130:131]
	s_cmp_lg_u32 s0, 1
	v_lshl_add_u64 v[2:3], s[22:23], 0, v[134:135]
	s_cbranch_scc1 .LBB0_831
	s_setprio 1
	s_barrier

; #define PG8_STAGE(bufoff, gbase, voff) do { _Pragma("unroll") for (int _i = 0; _i < 2; ++_i) \
;     __builtin_amdgcn_global_load_lds((const unsigned*)((const char*)(gbase) + (voff)[_i]), (LAS unsigned*)(lds + (bufoff) + ldsw + _i * 8192), 16, 0, 0); } while (0)
; #define PG8_BAR __builtin_amdgcn_s_barrier()
;   DI bool next(int i, Unit& u) const {
;     const long L = (long)i * G + c; if (L >= nwg) return false;
;     int wgid = (int)L; { const int q = nwg / NXCD, r = nwg % NXCD, xcd = wgid % NXCD, off = wgid / NXCD; wgid = (xcd < r ? xcd * (q + 1) : r * (q + 1) + (xcd - r) * q) + off; }
;     const int nig = wgm * nN, gid = wgid / nig, fm = gid * wgm, gsz = (nM - fm) < wgm ? (nM - fm) : wgm;
;     u.pm = fm + ((wgid % nig) % gsz); u.pn = (wgid % nig) / gsz; return true;
; template <class Epi>
; DI void gemm_phase(LAS unsigned char* lds, const Gemm g, const StaticOrder& S, const Epi& E) {
;     ...
;   bf16x8 At[4][2], B0[2][2], B1[2][2];
;   const char* cA = (const char*)g.A + (size_t)cur.pm * tstepA; const char* cB = (const char*)g.Bt + (size_t)cur.pn * tstepB;
;   PG8_STAGE(PG8_SB(0, 0), cB, voffB); PG8_STAGE(PG8_SA(0, 0), cA, voffA); PG8_STAGE(PG8_SB(0, 1), cB + hstepB, voffB); PG8_STAGE(PG8_SA(0, 1), cA + hstepA, voffA);
;   if (wr == 1) PG8_BAR;
.LBB0_911:
	s_ashr_i32 s0, s2, 3
	s_add_u32 s26, s84, 0x17800000
	s_addc_u32 s27, s85, 0
	s_add_u32 s28, s84, 0x1c80000
	s_addc_u32 s29, s85, 0
	s_add_i32 s0, s3, s0
	s_ashr_i32 s3, s0, 31
	s_lshr_b32 s3, s3, 25
	s_add_i32 s3, s0, s3
	s_ashr_i32 s4, s3, 7
	s_and_b32 s3, s3, 0xffffff80
	s_sub_i32 s3, s0, s3
	v_lshrrev_b32_e32 v3, 1, v10
	s_bfe_i32 s0, s3, 0x80000
	v_and_b32_e32 v15, 24, v3
	v_lshrrev_b32_e32 v3, 5, v10
	s_bfe_u32 s0, s0, 0x2000d
	v_and_b32_e32 v3, 4, v3
	v_bfe_u32 v4, v10, 2, 2
	s_add_i32 s5, s3, s0
	v_lshlrev_b32_e32 v1, 4, v10
	v_and_b32_e32 v2, 32, v10
	v_bfe_u32 v13, v10, 2, 4
	v_or3_b32 v3, v3, v4, v15
	v_lshrrev_b32_e32 v4, 3, v10
	s_movk_i32 s2, 0x70
	s_bfe_i32 s0, s5, 0x80000
	s_and_b32 s5, s5, 0xfc
	v_bitop3_b32 v11, v1, v2, 48 bitop3:0x6c
	v_and_b32_e32 v12, 64, v10
	v_and_or_b32 v5, v4, s2, v13
	s_movk_i32 s2, 0x60
	v_add_u32_e32 v14, 0x2000, v1
	s_sub_i32 s3, s3, s5
	v_or_b32_e32 v2, v11, v12
	v_and_or_b32 v4, v4, s2, v3
	v_lshrrev_b32_e32 v1, 7, v14
	s_movk_i32 s2, 0xf0
	s_lshl_b32 s4, s4, 2
	s_sext_i32_i16 s0, s0
	s_sext_i32_i8 s3, s3
	s_lshr_b32 s1, s24, 8
	v_lshl_or_b32 v132, v4, 12, v2
	v_and_or_b32 v4, v1, s2, v13
	s_movk_i32 s2, 0xe0
	s_lshr_b32 s0, s0, 2
	s_add_i32 s16, s4, s3
	v_and_or_b32 v1, v1, s2, v3
	s_lshr_b32 s2, s24, 6
	s_ashr_i32 s17, s16, 31
	s_bfe_i64 s[6:7], s[0:1], 0x100000
	s_lshl_b32 s30, s2, 10
	s_lshl_b64 s[4:5], s[16:17], 20
	s_lshl_b64 s[6:7], s[6:7], 20
	s_add_u32 s20, s28, s6
	s_addc_u32 s21, s29, s7
	s_add_i32 s17, s30, 0
	s_add_i32 m0, s17, 0x10000
	v_lshl_or_b32 v136, v1, 12, v2
	global_load_lds_dwordx4 v132, s[20:21]
	s_add_i32 m0, s17, 0x12000
	s_add_u32 s22, s26, s4
	v_lshl_or_b32 v130, v5, 12, v2
	global_load_lds_dwordx4 v136, s[20:21]
	s_addc_u32 s23, s27, s5
	s_mov_b32 m0, s17
	s_add_i32 s31, s17, 0x2000
	v_lshl_or_b32 v134, v4, 12, v2
	global_load_lds_dwordx4 v130, s[22:23]
	s_mov_b32 m0, s31
	s_add_u32 s4, s20, 0x80000
	global_load_lds_dwordx4 v134, s[22:23]
	s_addc_u32 s5, s21, 0
	s_add_i32 m0, s17, 0x14000
	v_mov_b32_e32 v139, 0
	global_load_lds_dwordx4 v132, s[4:5]
	s_add_i32 m0, s17, 0x16000
	v_mov_b32_e32 v133, v139
	global_load_lds_dwordx4 v136, s[4:5]
	s_add_u32 s4, s22, 0x80000
	s_addc_u32 s5, s23, 0
	s_add_i32 s33, s17, 0x4000
	s_mov_b32 m0, s33
	s_add_i32 s34, s17, 0x6000
	global_load_lds_dwordx4 v130, s[4:5]
	s_mov_b32 m0, s34
	v_mov_b32_e32 v137, v139
	global_load_lds_dwordx4 v134, s[4:5]
	v_mov_b32_e32 v131, v139
	v_mov_b32_e32 v135, v139
	s_mov_b32 s35, 0
	v_lshl_add_u64 v[8:9], s[20:21], 0, v[132:133]
	v_lshl_add_u64 v[6:7], s[20:21], 0, v[136:137]
	v_lshl_add_u64 v[4:5], s[22:23], 0, v[130:131]
	s_cmp_lg_u32 s1, 1
	v_lshl_add_u64 v[2:3], s[22:23], 0, v[134:135]
	s_cbranch_scc1 .LBB0_913
	s_setprio 1
	s_barrier

; #define PG8_STAGE(bufoff, gbase, voff) do { _Pragma("unroll") for (int _i = 0; _i < 2; ++_i) \
;     __builtin_amdgcn_global_load_lds((const unsigned*)((const char*)(gbase) + (voff)[_i]), (LAS unsigned*)(lds + (bufoff) + ldsw + _i * 8192), 16, 0, 0); } while (0)
; #define PG8_BAR __builtin_amdgcn_s_barrier()
; template <class Epi>
; DI void gemm_phase(LAS unsigned char* lds, const Gemm g, const StaticOrder& S, const Epi& E) {
;     ...
;   for (int i = 0; i < 2; ++i) { int R, C; stage_rc(tid * 16 + i * 8192, R, C); const int Rb = (R & ~31) + perm32(R & 31);
;     voffA[i] = (unsigned)(R * lda + C) * 2u; voffB[i] = (unsigned)(Rb * K + C) * 2u; }
;   const size_t kstep = (size_t)(BK * 2);
;   const size_t hstepA = (size_t)HALF * lda * 2, hstepB = (size_t)HALF * K * 2;
;   const size_t tstepA = 2 * hstepA, tstepB = 2 * hstepB;
;   const unsigned ldsw = (unsigned)wid * 1024u;
;   const int aoff = lds_byte(wr * 64 + fr, fq * 8), boff = lds_byte(wc * 32 + fr, fq * 8);
;     ...
;   bf16x8 At[4][2], B0[2][2], B1[2][2];
;   const char* cA = (const char*)g.A + (size_t)cur.pm * tstepA; const char* cB = (const char*)g.Bt + (size_t)cur.pn * tstepB;
;   PG8_STAGE(PG8_SB(0, 0), cB, voffB); PG8_STAGE(PG8_SA(0, 0), cA, voffA); PG8_STAGE(PG8_SB(0, 1), cB + hstepB, voffB); PG8_STAGE(PG8_SA(0, 1), cA + hstepA, voffA);
;   if (wr == 1) PG8_BAR;
.LBB0_950:
	s_andn2_b64 vcc, exec, s[0:1]
	s_cbranch_vccnz .LBB0_982
	v_lshrrev_b32_e32 v3, 1, v10
	v_lshrrev_b32_e32 v4, 5, v10
	v_and_b32_e32 v3, 24, v3
	v_and_b32_e32 v4, 4, v4
	v_bfe_u32 v5, v10, 2, 2
	s_add_u32 s27, s84, 0x6800000
	v_lshlrev_b32_e32 v1, 4, v10
	v_and_b32_e32 v2, 32, v10
	v_bfe_u32 v13, v10, 2, 4
	v_or3_b32 v3, v4, v5, v3
	v_lshrrev_b32_e32 v4, 3, v10
	s_movk_i32 s0, 0x70
	s_addc_u32 s28, s85, 0
	v_bitop3_b32 v11, v1, v2, 48 bitop3:0x6c
	v_and_b32_e32 v12, 64, v10
	v_and_or_b32 v5, v4, s0, v13
	s_movk_i32 s0, 0x60
	v_add_u32_e32 v14, 0x2000, v1
	s_add_u32 s29, s84, 0x3c80000
	v_or_b32_e32 v2, v11, v12
	v_and_or_b32 v4, v4, s0, v3
	v_lshrrev_b32_e32 v1, 7, v14
	s_movk_i32 s0, 0xf0
	s_addc_u32 s30, s85, 0
	s_lshr_b32 s1, s26, 6
	v_lshl_or_b32 v132, v4, 14, v2
	v_and_or_b32 v4, v1, s0, v13
	s_movk_i32 s0, 0xe0
	s_ashr_i32 s19, s18, 31
	s_ashr_i32 s5, s4, 31
	v_and_or_b32 v1, v1, s0, v3
	s_lshr_b32 s0, s26, 8
	s_lshl_b32 s31, s1, 10
	s_lshl_b64 s[2:3], s[18:19], 22
	s_lshl_b64 s[6:7], s[4:5], 22
	s_add_u32 s22, s29, s6
	s_addc_u32 s23, s30, s7
	s_add_i32 s33, s31, 0
	s_add_i32 m0, s33, 0x10000
	v_lshl_or_b32 v136, v1, 14, v2
	global_load_lds_dwordx4 v132, s[22:23]
	s_add_i32 m0, s33, 0x12000
	s_add_u32 s20, s27, s2
	v_lshl_or_b32 v130, v5, 14, v2
	global_load_lds_dwordx4 v136, s[22:23]
	s_addc_u32 s21, s28, s3
	s_mov_b32 m0, s33
	s_add_i32 s34, s33, 0x2000
	v_lshl_or_b32 v134, v4, 14, v2
	global_load_lds_dwordx4 v130, s[20:21]
	s_mov_b32 m0, s34
	s_add_u32 s2, s22, 0x200000
	global_load_lds_dwordx4 v134, s[20:21]
	s_addc_u32 s3, s23, 0
	s_add_i32 m0, s33, 0x14000
	v_mov_b32_e32 v139, 0
	global_load_lds_dwordx4 v132, s[2:3]
	s_add_i32 m0, s33, 0x16000
	v_mov_b32_e32 v133, v139
	global_load_lds_dwordx4 v136, s[2:3]
	s_add_u32 s2, s20, 0x200000
	s_addc_u32 s3, s21, 0
	s_add_i32 s35, s33, 0x4000
	s_mov_b32 m0, s35
	s_add_i32 s36, s33, 0x6000
	global_load_lds_dwordx4 v130, s[2:3]
	s_mov_b32 m0, s36
	v_mov_b32_e32 v137, v139
	global_load_lds_dwordx4 v134, s[2:3]
	v_mov_b32_e32 v131, v139
	v_mov_b32_e32 v135, v139
	s_mov_b32 s5, 0
	v_lshl_add_u64 v[8:9], s[22:23], 0, v[132:133]
	v_lshl_add_u64 v[6:7], s[22:23], 0, v[136:137]
	v_lshl_add_u64 v[4:5], s[20:21], 0, v[130:131]
	s_cmp_lg_u32 s0, 1
	v_lshl_add_u64 v[2:3], s[20:21], 0, v[134:135]
	s_cbranch_scc1 .LBB0_953
	s_setprio 1
	s_barrier

; #define PG8_STAGE(bufoff, gbase, voff) do { _Pragma("unroll") for (int _i = 0; _i < 2; ++_i) \
;     __builtin_amdgcn_global_load_lds((const unsigned*)((const char*)(gbase) + (voff)[_i]), (LAS unsigned*)(lds + (bufoff) + ldsw + _i * 8192), 16, 0, 0); } while (0)
; #define PG8_BAR __builtin_amdgcn_s_barrier()
;   DI bool next(int i, Unit& u) const {
;     const long L = (long)i * G + c; if (L >= nwg) return false;
;     int wgid = (int)L; { const int q = nwg / NXCD, r = nwg % NXCD, xcd = wgid % NXCD, off = wgid / NXCD; wgid = (xcd < r ? xcd * (q + 1) : r * (q + 1) + (xcd - r) * q) + off; }
;     const int nig = wgm * nN, gid = wgid / nig, fm = gid * wgm, gsz = (nM - fm) < wgm ? (nM - fm) : wgm;
;     u.pm = fm + ((wgid % nig) % gsz); u.pn = (wgid % nig) / gsz; return true;
; template <class Epi>
; DI void gemm_phase(LAS unsigned char* lds, const Gemm g, const StaticOrder& S, const Epi& E) {
;     ...
;   bf16x8 At[4][2], B0[2][2], B1[2][2];
;   const char* cA = (const char*)g.A + (size_t)cur.pm * tstepA; const char* cB = (const char*)g.Bt + (size_t)cur.pn * tstepB;
;   PG8_STAGE(PG8_SB(0, 0), cB, voffB); PG8_STAGE(PG8_SA(0, 0), cA, voffA); PG8_STAGE(PG8_SB(0, 1), cB + hstepB, voffB); PG8_STAGE(PG8_SA(0, 1), cA + hstepA, voffA);
;   if (wr == 1) PG8_BAR;
.LBB0_1005:
	s_ashr_i32 s0, s2, 3
	s_add_u32 s26, s84, 0x1b800000
	s_addc_u32 s27, s85, 0
	s_add_u32 s28, s84, 0x1c80000
	s_addc_u32 s29, s85, 0
	s_add_i32 s0, s3, s0
	s_ashr_i32 s3, s0, 31
	s_lshr_b32 s3, s3, 25
	s_add_i32 s3, s0, s3
	s_ashr_i32 s4, s3, 7
	s_and_b32 s3, s3, 0xffffff80
	s_sub_i32 s3, s0, s3
	v_lshrrev_b32_e32 v3, 1, v10
	s_bfe_i32 s0, s3, 0x80000
	v_and_b32_e32 v15, 24, v3
	v_lshrrev_b32_e32 v3, 5, v10
	s_bfe_u32 s0, s0, 0x2000d
	v_and_b32_e32 v3, 4, v3
	v_bfe_u32 v4, v10, 2, 2
	s_add_i32 s5, s3, s0
	v_lshlrev_b32_e32 v1, 4, v10
	v_and_b32_e32 v2, 32, v10
	v_bfe_u32 v13, v10, 2, 4
	v_or3_b32 v3, v3, v4, v15
	v_lshrrev_b32_e32 v4, 3, v10
	s_movk_i32 s2, 0x70
	s_bfe_i32 s0, s5, 0x80000
	s_and_b32 s5, s5, 0xfc
	v_bitop3_b32 v11, v1, v2, 48 bitop3:0x6c
	v_and_b32_e32 v12, 64, v10
	v_and_or_b32 v5, v4, s2, v13
	s_movk_i32 s2, 0x60
	v_add_u32_e32 v14, 0x2000, v1
	s_sub_i32 s3, s3, s5
	v_or_b32_e32 v2, v11, v12
	v_and_or_b32 v4, v4, s2, v3
	v_lshrrev_b32_e32 v1, 7, v14
	s_movk_i32 s2, 0xf0
	s_lshl_b32 s4, s4, 2
	s_sext_i32_i16 s0, s0
	s_sext_i32_i8 s3, s3
	s_lshr_b32 s1, s24, 8
	v_lshl_or_b32 v132, v4, 12, v2
	v_and_or_b32 v4, v1, s2, v13
	s_movk_i32 s2, 0xe0
	s_lshr_b32 s0, s0, 2
	s_add_i32 s16, s4, s3
	v_and_or_b32 v1, v1, s2, v3
	s_lshr_b32 s2, s24, 6
	s_ashr_i32 s17, s16, 31
	s_bfe_i64 s[6:7], s[0:1], 0x100000
	s_lshl_b32 s30, s2, 10
	s_lshl_b64 s[4:5], s[16:17], 20
	s_lshl_b64 s[6:7], s[6:7], 20
	s_add_u32 s20, s28, s6
	s_addc_u32 s21, s29, s7
	s_add_i32 s17, s30, 0
	s_add_i32 m0, s17, 0x10000
	v_lshl_or_b32 v136, v1, 12, v2
	global_load_lds_dwordx4 v132, s[20:21]
	s_add_i32 m0, s17, 0x12000
	s_add_u32 s22, s26, s4
	v_lshl_or_b32 v130, v5, 12, v2
	global_load_lds_dwordx4 v136, s[20:21]
	s_addc_u32 s23, s27, s5
	s_mov_b32 m0, s17
	s_add_i32 s31, s17, 0x2000
	v_lshl_or_b32 v134, v4, 12, v2
	global_load_lds_dwordx4 v130, s[22:23]
	s_mov_b32 m0, s31
	s_add_u32 s4, s20, 0x80000
	global_load_lds_dwordx4 v134, s[22:23]
	s_addc_u32 s5, s21, 0
	s_add_i32 m0, s17, 0x14000
	v_mov_b32_e32 v139, 0
	global_load_lds_dwordx4 v132, s[4:5]
	s_add_i32 m0, s17, 0x16000
	v_mov_b32_e32 v133, v139
	global_load_lds_dwordx4 v136, s[4:5]
	s_add_u32 s4, s22, 0x80000
	s_addc_u32 s5, s23, 0
	s_add_i32 s33, s17, 0x4000
	s_mov_b32 m0, s33
	s_add_i32 s34, s17, 0x6000
	global_load_lds_dwordx4 v130, s[4:5]
	s_mov_b32 m0, s34
	v_mov_b32_e32 v137, v139
	global_load_lds_dwordx4 v134, s[4:5]
	v_mov_b32_e32 v131, v139
	v_mov_b32_e32 v135, v139
	s_mov_b32 s35, 0
	v_lshl_add_u64 v[8:9], s[20:21], 0, v[132:133]
	v_lshl_add_u64 v[6:7], s[20:21], 0, v[136:137]
	v_lshl_add_u64 v[4:5], s[22:23], 0, v[130:131]
	s_cmp_lg_u32 s1, 1
	v_lshl_add_u64 v[2:3], s[22:23], 0, v[134:135]
	s_cbranch_scc1 .LBB0_1007
	s_setprio 1
	s_barrier
